# phase 0 row loop: b_in[lane] loaded once before the loop instead of per row with a full vmcnt(0) wait (on top of the LN3 prefetch variant)
# speedup vs baseline: 1.0135x; 1.0046x over previous
; #define LAS __attribute__((address_space(3)))
; __device__ __forceinline__ void stage_wig(CArgs& A, Frame& F, int L) {
;     const float* w_in = A.in[9] + (size_t)L * D * DIN; LAS float* wig = (LAS float*)(F.lds + WIG_OFF);
;     float t[16];
; #pragma unroll
;     for (int q = 0; q < 16; ++q) { const int i = F.tid + NT * q; t[q] = w_in[(size_t)(i >> 3) * DIN + 3072 + (i & 7)]; }
; #pragma unroll
;     for (int q = 0; q < 16; ++q) { const int i = F.tid + NT * q; wig[(i & 7) * 1024 + (i >> 3)] = t[q]; }
; }
; __global__ void __launch_bounds__(NT, 2) fwd(const Args args) {
;     ...
;         stage_wig(A, F, 0); __syncthreads();
.LBB0_7:
	s_lshr_b32 s0, s4, 6
	v_writelane_b32 v253, s0, 11
	s_lshl_b32 s96, s94, 3
	v_readlane_b32 s0, v253, 1
	v_readlane_b32 s2, v253, 3
	v_readlane_b32 s1, v253, 2
	v_readlane_b32 s3, v253, 4
	s_cmp_lt_i32 s2, 1
	s_cselect_b64 s[0:1], -1, 0
	s_cmp_gt_i32 s3, 0
	s_cselect_b64 s[2:3], -1, 0
	s_and_b64 s[0:1], s[0:1], s[2:3]
	s_andn2_b64 vcc, exec, s[0:1]
	s_cbranch_vccnz .LBB0_45
	v_readlane_b32 s20, v253, 5
	v_readlane_b32 s21, v253, 6
	s_mov_b32 s2, 0
	s_mov_b32 s4, 0
	s_load_dwordx2 s[2:3], s[20:21], 0xe8
	v_readlane_b32 s23, v253, 11
	v_mbcnt_lo_u32_b32 v1, -1, s4
	v_readlane_b32 s4, v253, 0
	v_mbcnt_hi_u32_b32 v38, -1, v1
	s_mov_b32 s22, s4
	s_load_dwordx2 s[24:25], s[20:21], 0x48
	v_lshl_add_u32 v34, s23, 6, v38
	v_and_b32_e32 v1, 7, v38
	v_ashrrev_i32_e32 v20, 3, v34
	s_movk_i32 s6, 0x6820
	s_waitcnt lgkmcnt(0)
	v_mov_b64_e32 v[2:3], s[24:25]
	v_mad_i64_i32 v[4:5], s[4:5], v20, s6, v[2:3]
	v_lshlrev_b32_e32 v36, 2, v1
	v_mov_b32_e32 v37, 0
	v_add_u32_e32 v6, 0x200, v34
	v_lshl_add_u64 v[4:5], v[4:5], 0, v[36:37]
	s_movk_i32 s7, 0x3000
	v_ashrrev_i32_e32 v21, 3, v6
	v_add_co_u32_e32 v4, vcc, s7, v4
	v_mad_i64_i32 v[6:7], s[4:5], v21, s6, v[2:3]
	v_add_u32_e32 v8, 0x400, v34
	v_addc_co_u32_e32 v5, vcc, 0, v5, vcc
	v_lshl_add_u64 v[6:7], v[6:7], 0, v[36:37]
	v_ashrrev_i32_e32 v22, 3, v8
	v_add_co_u32_e32 v6, vcc, s7, v6
	v_mad_i64_i32 v[8:9], s[4:5], v22, s6, v[2:3]
	v_add_u32_e32 v10, 0x600, v34
	v_addc_co_u32_e32 v7, vcc, 0, v7, vcc
	v_lshl_add_u64 v[8:9], v[8:9], 0, v[36:37]
	v_ashrrev_i32_e32 v23, 3, v10
	v_add_co_u32_e32 v8, vcc, s7, v8
	v_mad_i64_i32 v[10:11], s[4:5], v23, s6, v[2:3]
	v_add_u32_e32 v12, 0x800, v34
	v_addc_co_u32_e32 v9, vcc, 0, v9, vcc
	v_lshl_add_u64 v[10:11], v[10:11], 0, v[36:37]
	v_ashrrev_i32_e32 v24, 3, v12
	v_add_co_u32_e32 v10, vcc, s7, v10
	v_mad_i64_i32 v[12:13], s[4:5], v24, s6, v[2:3]
	v_add_u32_e32 v14, 0xa00, v34
	v_addc_co_u32_e32 v11, vcc, 0, v11, vcc
	v_lshl_add_u64 v[12:13], v[12:13], 0, v[36:37]
	v_ashrrev_i32_e32 v25, 3, v14
	v_add_co_u32_e32 v12, vcc, s7, v12
	v_mad_i64_i32 v[14:15], s[4:5], v25, s6, v[2:3]
	v_add_u32_e32 v16, 0xc00, v34
	v_addc_co_u32_e32 v13, vcc, 0, v13, vcc
	v_lshl_add_u64 v[14:15], v[14:15], 0, v[36:37]
	v_ashrrev_i32_e32 v26, 3, v16
	v_add_co_u32_e32 v14, vcc, s7, v14
	v_mad_i64_i32 v[16:17], s[4:5], v26, s6, v[2:3]
	v_add_u32_e32 v18, 0xe00, v34
	v_addc_co_u32_e32 v15, vcc, 0, v15, vcc
	v_lshl_add_u64 v[16:17], v[16:17], 0, v[36:37]
	v_ashrrev_i32_e32 v27, 3, v18
	v_add_co_u32_e32 v16, vcc, s7, v16
	v_mad_i64_i32 v[18:19], s[4:5], v27, s6, v[2:3]
	s_nop 0
	v_addc_co_u32_e32 v17, vcc, 0, v17, vcc
	v_lshl_add_u64 v[18:19], v[18:19], 0, v[36:37]
	v_add_co_u32_e32 v18, vcc, s7, v18
	s_nop 1
	v_addc_co_u32_e32 v19, vcc, 0, v19, vcc
	global_load_dword v28, v[4:5], off
	global_load_dword v29, v[6:7], off
	global_load_dword v30, v[8:9], off
	global_load_dword v31, v[10:11], off
	global_load_dword v32, v[12:13], off
	global_load_dword v33, v[14:15], off
	global_load_dword v35, v[16:17], off
	global_load_dword v39, v[18:19], off
	v_add_u32_e32 v4, 0x1000, v34
	v_ashrrev_i32_e32 v16, 3, v4
	v_mad_i64_i32 v[4:5], s[4:5], v16, s6, v[2:3]
	v_lshl_add_u64 v[4:5], v[4:5], 0, v[36:37]
	v_add_co_u32_e32 v4, vcc, s7, v4
	v_add_u32_e32 v6, 0x1400, v34
	s_nop 0
	v_addc_co_u32_e32 v5, vcc, 0, v5, vcc
	global_load_dword v17, v[4:5], off
	v_add_u32_e32 v4, 0x1200, v34
	v_ashrrev_i32_e32 v18, 3, v4
	v_mad_i64_i32 v[4:5], s[4:5], v18, s6, v[2:3]
	v_lshl_add_u64 v[4:5], v[4:5], 0, v[36:37]
	v_ashrrev_i32_e32 v19, 3, v6
	v_add_co_u32_e32 v4, vcc, s7, v4
	v_mad_i64_i32 v[6:7], s[4:5], v19, s6, v[2:3]
	v_add_u32_e32 v8, 0x1600, v34
	v_addc_co_u32_e32 v5, vcc, 0, v5, vcc
	v_lshl_add_u64 v[6:7], v[6:7], 0, v[36:37]
	v_ashrrev_i32_e32 v40, 3, v8
	v_add_co_u32_e32 v6, vcc, s7, v6
	v_mad_i64_i32 v[8:9], s[4:5], v40, s6, v[2:3]
	v_add_u32_e32 v10, 0x1800, v34
	v_addc_co_u32_e32 v7, vcc, 0, v7, vcc
	v_lshl_add_u64 v[8:9], v[8:9], 0, v[36:37]
	v_ashrrev_i32_e32 v41, 3, v10
	v_add_co_u32_e32 v8, vcc, s7, v8
	v_mad_i64_i32 v[10:11], s[4:5], v41, s6, v[2:3]
	v_add_u32_e32 v12, 0x1a00, v34
	v_addc_co_u32_e32 v9, vcc, 0, v9, vcc
	v_lshl_add_u64 v[10:11], v[10:11], 0, v[36:37]
	v_ashrrev_i32_e32 v42, 3, v12
	v_add_co_u32_e32 v10, vcc, s7, v10
	v_mad_i64_i32 v[12:13], s[4:5], v42, s6, v[2:3]
	v_add_u32_e32 v14, 0x1c00, v34
	v_addc_co_u32_e32 v11, vcc, 0, v11, vcc
	v_lshl_add_u64 v[12:13], v[12:13], 0, v[36:37]
	v_ashrrev_i32_e32 v43, 3, v14
	v_add_co_u32_e32 v12, vcc, s7, v12
	v_mad_i64_i32 v[14:15], s[4:5], v43, s6, v[2:3]
	s_nop 0
	v_addc_co_u32_e32 v13, vcc, 0, v13, vcc
	v_lshl_add_u64 v[14:15], v[14:15], 0, v[36:37]
	v_add_co_u32_e32 v14, vcc, s7, v14
	s_nop 1
	v_addc_co_u32_e32 v15, vcc, 0, v15, vcc
	global_load_dword v44, v[4:5], off
	global_load_dword v45, v[6:7], off
	global_load_dword v46, v[8:9], off
	global_load_dword v47, v[10:11], off
	global_load_dword v48, v[12:13], off
	global_load_dword v49, v[14:15], off
	v_add_u32_e32 v4, 0x1e00, v34
	v_ashrrev_i32_e32 v4, 3, v4
	v_mad_i64_i32 v[2:3], s[4:5], v4, s6, v[2:3]
	v_lshl_add_u64 v[2:3], v[2:3], 0, v[36:37]
	v_add_co_u32_e32 v2, vcc, s7, v2
	s_lshl_b32 s4, s22, 3
	s_nop 0
	v_addc_co_u32_e32 v3, vcc, 0, v3, vcc
	global_load_dword v2, v[2:3], off
	v_lshlrev_b32_e32 v3, 12, v38
	s_add_i32 s26, s4, s23
	s_add_i32 s4, 0, 0x12000
	v_and_b32_e32 v3, 0x7000, v3
	v_add_u32_e32 v3, s4, v3
	v_lshl_add_u32 v5, v20, 2, v3
	s_waitcnt vmcnt(15)
	ds_write_b32 v5, v28
	v_lshl_add_u32 v5, v21, 2, v3
	s_waitcnt vmcnt(14)
	ds_write_b32 v5, v29
	v_lshl_add_u32 v5, v22, 2, v3
	s_waitcnt vmcnt(13)
	ds_write_b32 v5, v30
	v_lshl_add_u32 v5, v23, 2, v3
	s_waitcnt vmcnt(12)
	ds_write_b32 v5, v31
	v_lshl_add_u32 v5, v24, 2, v3
	s_waitcnt vmcnt(11)
	ds_write_b32 v5, v32
	v_lshl_add_u32 v5, v25, 2, v3
	s_waitcnt vmcnt(10)
	ds_write_b32 v5, v33
	v_lshl_add_u32 v5, v26, 2, v3
	s_waitcnt vmcnt(9)
	ds_write_b32 v5, v35
	v_lshl_add_u32 v5, v27, 2, v3
	s_waitcnt vmcnt(8)
	ds_write_b32 v5, v39
	v_lshl_add_u32 v5, v16, 2, v3
	s_waitcnt vmcnt(7)
	ds_write_b32 v5, v17
	v_lshl_add_u32 v5, v18, 2, v3
	s_abs_i32 s4, s96
	v_cvt_f32_u32_e32 v6, s4
	s_sub_i32 s6, 0, s4
	s_ashr_i32 s5, s96, 31
	s_waitcnt vmcnt(6)
	ds_write_b32 v5, v44
	v_lshl_add_u32 v5, v19, 2, v3
	s_waitcnt vmcnt(5)
	ds_write_b32 v5, v45
	v_lshl_add_u32 v5, v40, 2, v3
	s_waitcnt vmcnt(4)
	ds_write_b32 v5, v46
	v_lshl_add_u32 v5, v41, 2, v3
	s_waitcnt vmcnt(3)
	ds_write_b32 v5, v47
	v_lshl_add_u32 v5, v42, 2, v3
	s_waitcnt vmcnt(2)
	ds_write_b32 v5, v48
	v_lshl_add_u32 v5, v43, 2, v3
	s_waitcnt vmcnt(1)
	ds_write_b32 v5, v49
	v_rcp_iflag_f32_e32 v5, v6
	v_lshl_add_u32 v3, v4, 2, v3
	s_waitcnt vmcnt(0)
	ds_write_b32 v3, v2
	v_mul_f32_e32 v2, 0x4f7ffffe, v5
	v_cvt_u32_f32_e32 v2, v2
	s_waitcnt lgkmcnt(0)
	s_barrier
; __global__ void __launch_bounds__(NT, 2) fwd(const Args args) {
;     ...
;         { int m0, m1; row_range(F, m0, m1);
;           for (int m = m0; m < m1; m += 2) { const int mb = (m + 1 < m1) ? m + 1 : m; f32x4 va[4], vb[4];
;               row_load(m < TP ? A.in[0] + (size_t)m * D : A.in[1] + (size_t)(m - TP) * D, F.lane, va); row_load(mb < TP ? A.in[0] + (size_t)mb * D : A.in[1] + (size_t)(mb - TP) * D, F.lane, vb);
	v_readfirstlane_b32 s7, v2
	s_mul_i32 s6, s6, s7
	s_mul_hi_u32 s6, s7, s6
	s_add_i32 s7, s7, s6
	s_mul_hi_u32 s6, s7, 0x4200
	s_mul_i32 s7, s6, s4
	s_sub_i32 s7, 0x4200, s7
	s_sub_i32 s8, s7, s4
	s_add_i32 s9, s6, 1
	s_cmp_ge_u32 s7, s4
	s_cselect_b32 s7, s8, s7
	s_cselect_b32 s6, s9, s6
	s_sub_i32 s8, s7, s4
	s_add_i32 s9, s6, 1
	s_cmp_ge_u32 s7, s4
	s_cselect_b32 s4, s9, s6
	s_cselect_b32 s28, s8, s7
	s_xor_b32 s4, s4, s5
	s_sub_i32 s7, s4, s5
	s_min_i32 s6, s26, s28
	s_mul_i32 s30, s7, s26
	s_add_i32 s6, s30, s6
	s_cmp_lt_i32 s26, s28
	s_cselect_b64 s[4:5], -1, 0
	s_cmp_lg_u64 s[4:5], 0
	s_addc_u32 s38, s6, s7
	s_cmp_ge_i32 s6, s38
	s_cbranch_scc1 .LBB0_15
	v_lshlrev_b32_e32 v2, 3, v38
	s_load_dwordx2 s[18:19], s[20:21], 0x50
	v_ashrrev_i32_e32 v3, 31, v2
	v_lshlrev_b64 v[4:5], 1, v[2:3]
	v_lshl_add_u64 v[6:7], s[2:3], 0, v[4:5]
	s_mov_b64 s[34:35], 0x7680000
	v_ashrrev_i32_e32 v39, 31, v38
	v_lshl_add_u64 v[40:41], v[6:7], 0, s[34:35]
	v_lshlrev_b64 v[6:7], 2, v[38:39]
	s_waitcnt lgkmcnt(0)
	v_lshl_add_u64 v[8:9], s[18:19], 0, v[6:7]
	s_mov_b64 s[18:19], 0x3000
	v_lshl_add_u64 v[42:43], v[8:9], 0, s[18:19]
	global_load_dword v149, v[42:43], off
	v_lshl_add_u64 v[8:9], s[2:3], 0, v[6:7]
	s_mov_b64 s[36:37], 0x1b000000
	s_ashr_i32 s27, s26, 31
	v_lshl_add_u64 v[44:45], v[8:9], 0, s[36:37]
	s_ashr_i32 s29, s28, 31
	v_mov_b64_e32 v[8:9], s[26:27]
	v_cmp_lt_i64_e64 s[18:19], s[28:29], v[8:9]
	s_and_b64 s[18:19], s[18:19], exec
	s_cselect_b32 s19, s29, s27
	s_cselect_b32 s18, s28, s26
	s_ashr_i32 s27, s30, 31
	s_add_u32 s18, s18, s30
	s_addc_u32 s19, s19, s27
	s_lshl_b64 s[28:29], s[18:19], 11
	s_add_u32 s28, s2, s28
	s_addc_u32 s29, s3, s29
	v_lshl_add_u64 v[4:5], s[28:29], 0, v[4:5]
	s_lshl_b64 s[28:29], s[18:19], 5
	s_add_u32 s28, s2, s28
	s_addc_u32 s29, s3, s29
	v_lshlrev_b32_e32 v10, 5, v38
	v_lshl_add_u64 v[46:47], v[4:5], 0, s[34:35]
	v_lshl_add_u64 v[4:5], s[28:29], 0, v[6:7]
	v_cmp_gt_i32_e32 vcc, 8, v38
	v_cmp_eq_u32_e64 s[16:17], 1, v38
	v_cmp_eq_u32_e64 s[4:5], 2, v38
	v_cmp_eq_u32_e64 s[6:7], 3, v38
	v_cmp_eq_u32_e64 s[8:9], 4, v38
	v_cmp_eq_u32_e64 s[10:11], 5, v38
	v_cmp_eq_u32_e64 s[12:13], 6, v38
	v_cmp_eq_u32_e64 s[14:15], 7, v38
	v_lshl_add_u64 v[48:49], v[4:5], 0, s[36:37]
	s_mov_b64 s[28:29], 0
	v_lshlrev_b64 v[50:51], 2, v[2:3]
	s_mov_b64 s[30:31], 0x1000
	v_add_u32_e32 v35, 0, v10
	s_branch .LBB0_11

; #define LAS __attribute__((address_space(3)))
; __device__ __forceinline__ float wave_sum(float v) { return rdlane(dpp_sum63(v), 63); }
; __device__ __forceinline__ void row_finalize(CArgs& A, Frame& F, int m, const f32x4 (&v)[4], int Ln) {
;     row_store_bf(WSP(bf16, WS_X) + (size_t)m * D, F.lane, v);
;     const LAS float* wig = (const LAS float*)(F.lds + WIG_OFF); const float* b_in = A.in[10] + (size_t)Ln * DIN + 3072;
;     float r[8];
; #pragma unroll
;     for (int c = 0; c < 8; ++c) { float s = 0.f;
; #pragma unroll
;         for (int j = 0; j < 4; ++j) { const f32x4 w = *(const LAS f32x4*)(wig + c * 1024 + RCOL(F.lane, j)); s += (v[j][0] * w[0] + v[j][1] * w[1]) + (v[j][2] * w[2] + v[j][3] * w[3]); }
;         r[c] = wave_sum(s); if (c & 1) asm volatile("" ::: "memory"); }
; __global__ void __launch_bounds__(NT, 2) fwd(const Args args) {
;     ...
;           for (int m = m0; m < m1; m += 2) { const int mb = (m + 1 < m1) ? m + 1 : m; f32x4 va[4], vb[4];
;               row_load(m < TP ? A.in[0] + (size_t)m * D : A.in[1] + (size_t)(m - TP) * D, F.lane, va); row_load(mb < TP ? A.in[0] + (size_t)mb * D : A.in[1] + (size_t)(mb - TP) * D, F.lane, vb);
;               row_finalize(A, F, m, va, 0); row_finalize(A, F, mb, vb, 0); } }
.LBB0_11:
	s_add_u32 s27, s18, s28
	s_addc_u32 s35, s19, s29
	s_add_i32 s34, s27, 1
	s_cmp_lt_i32 s34, s38
	s_cselect_b32 s34, s34, s27
	s_add_i32 s36, s27, 0xffffc000
	s_cmpk_lt_i32 s27, 0x4000
	s_cselect_b32 s36, s27, s36
	s_cselect_b32 s27, 0, 8
	s_cselect_b32 s37, s35, 0
	s_add_u32 s40, s20, s27
	s_addc_u32 s41, s21, 0
	s_load_dwordx2 s[40:41], s[40:41], 0x0
	s_lshl_b64 s[36:37], s[36:37], 12
	v_add_u32_e32 v39, 0x12000, v35
	v_add_u32_e32 v37, 0x13000, v35
	v_mov_b32_e32 v88, 0
	s_waitcnt lgkmcnt(0)
	s_add_u32 s36, s40, s36
	s_addc_u32 s37, s41, s37
	v_lshl_add_u64 v[2:3], s[36:37], 0, v[50:51]
	global_load_dwordx4 v[30:33], v[2:3], off
	global_load_dwordx4 v[26:29], v[2:3], off offset:16
	global_load_dwordx4 v[22:25], v[2:3], off offset:2048
	global_load_dwordx4 v[18:21], v[2:3], off offset:2064
	s_add_i32 s27, s34, 0xffffc000
	s_ashr_i32 s35, s34, 31
	s_cmpk_lt_i32 s34, 0x4000
	s_cselect_b32 s36, s34, s27
	s_cselect_b32 s27, 0, 8
	s_cselect_b32 s37, s35, 0
	s_add_u32 s40, s20, s27
	s_addc_u32 s41, s21, 0
	s_load_dwordx2 s[40:41], s[40:41], 0x0
	s_lshl_b64 s[36:37], s[36:37], 12
	v_mov_b32_e32 v89, 0
	s_waitcnt lgkmcnt(0)
	s_add_u32 s36, s40, s36
	s_addc_u32 s37, s41, s37
	v_lshl_add_u64 v[52:53], s[36:37], 0, v[50:51]
	global_load_dwordx4 v[10:13], v[52:53], off offset:16
	global_load_dwordx4 v[14:17], v[52:53], off
	global_load_dwordx4 v[2:5], v[52:53], off offset:2064
	global_load_dwordx4 v[6:9], v[52:53], off offset:2048
	s_waitcnt vmcnt(7)
	v_cvt_pk_bf16_f32 v52, v30, v31
	v_cvt_pk_bf16_f32 v53, v32, v33
	s_waitcnt vmcnt(6)
	v_cvt_pk_bf16_f32 v54, v26, v27
	v_cvt_pk_bf16_f32 v55, v28, v29
	global_store_dwordx4 v[46:47], v[52:55], off
	s_waitcnt vmcnt(6)
	s_nop 0
	v_cvt_pk_bf16_f32 v52, v22, v23
	v_cvt_pk_bf16_f32 v53, v24, v25
	s_waitcnt vmcnt(5)
	v_cvt_pk_bf16_f32 v54, v18, v19
	v_cvt_pk_bf16_f32 v55, v20, v21
	ds_read_b128 v[56:59], v39
	ds_read_b128 v[60:63], v39 offset:16
	ds_read_b128 v[64:67], v39 offset:2048
	ds_read_b128 v[68:71], v39 offset:2064
	ds_read_b128 v[72:75], v37
	ds_read_b128 v[76:79], v37 offset:16
	ds_read_b128 v[80:83], v37 offset:2048
	ds_read_b128 v[84:87], v37 offset:2064
	global_store_dwordx4 v[46:47], v[52:55], off offset:1024
	s_waitcnt lgkmcnt(7)
	s_nop 0
	v_mul_f32_e32 v52, v31, v57
	v_mul_f32_e32 v53, v33, v59
	s_waitcnt lgkmcnt(6)
	v_mul_f32_e32 v54, v27, v61
	v_mul_f32_e32 v55, v29, v63
	v_fmac_f32_e32 v52, v30, v56
	v_fmac_f32_e32 v53, v32, v58
	s_waitcnt lgkmcnt(5)
	v_mul_f32_e32 v57, v23, v65
	v_mul_f32_e32 v59, v25, v67
	v_fmac_f32_e32 v54, v26, v60
	v_fmac_f32_e32 v55, v28, v62
	v_add_f32_e32 v52, v52, v53
	s_waitcnt lgkmcnt(4)
	v_mul_f32_e32 v61, v19, v69
	v_mul_f32_e32 v63, v21, v71
	v_fmac_f32_e32 v57, v22, v64
	v_fmac_f32_e32 v59, v24, v66
	v_add_f32_e32 v53, v54, v55
	v_add_f32_e32 v52, 0, v52
	v_fmac_f32_e32 v61, v18, v68
	v_fmac_f32_e32 v63, v20, v70
	v_add_f32_e32 v54, v57, v59
	v_add_f32_e32 v52, v52, v53
	v_add_f32_e32 v55, v61, v63
	v_add_f32_e32 v52, v52, v54
	v_add_f32_e32 v52, v52, v55
	s_waitcnt lgkmcnt(3)
	v_mul_f32_e32 v65, v31, v73
	v_mul_f32_e32 v67, v33, v75
	v_add_f32_dpp v52, v52, v52 quad_perm:[1,0,3,2] row_mask:0xf bank_mask:0xf bound_ctrl:1
	s_waitcnt lgkmcnt(2)
	v_mul_f32_e32 v69, v27, v77
	v_mul_f32_e32 v71, v29, v79
	v_fmac_f32_e32 v65, v30, v72
	v_fmac_f32_e32 v67, v32, v74
	v_add_f32_dpp v52, v52, v52 quad_perm:[2,3,0,1] row_mask:0xf bank_mask:0xf bound_ctrl:1
	s_waitcnt lgkmcnt(1)
	v_mul_f32_e32 v73, v23, v81
	v_mul_f32_e32 v75, v25, v83
	v_fmac_f32_e32 v69, v26, v76
	v_fmac_f32_e32 v71, v28, v78
	v_add_f32_e32 v56, v65, v67
	v_add_f32_dpp v52, v52, v52 row_half_mirror row_mask:0xf bank_mask:0xf bound_ctrl:1
	s_waitcnt lgkmcnt(0)
	v_mul_f32_e32 v77, v19, v85
	v_mul_f32_e32 v79, v21, v87
	v_fmac_f32_e32 v73, v22, v80
	v_fmac_f32_e32 v75, v24, v82
	v_add_f32_e32 v57, v69, v71
	v_add_f32_e32 v56, 0, v56
	v_add_f32_dpp v52, v52, v52 row_mirror row_mask:0xf bank_mask:0xf bound_ctrl:1
	v_fmac_f32_e32 v77, v18, v84
	v_fmac_f32_e32 v79, v20, v86
	v_add_f32_e32 v58, v73, v75
	v_add_f32_e32 v53, v56, v57
	v_mov_b32_dpp v88, v52 row_bcast:15 row_mask:0xa bank_mask:0xf
	v_add_f32_e32 v59, v77, v79
	v_add_f32_e32 v53, v53, v58
	v_add_f32_e32 v52, v52, v88
	v_add_f32_e32 v53, v53, v59
	v_add_u32_e32 v56, 0x14000, v35
	v_mov_b32_dpp v89, v52 row_bcast:31 row_mask:0xc bank_mask:0xf
	v_add_f32_dpp v53, v53, v53 quad_perm:[1,0,3,2] row_mask:0xf bank_mask:0xf bound_ctrl:1
	v_add_f32_e32 v52, v52, v89
	s_nop 0
	v_readlane_b32 s27, v52, 63
	v_add_f32_dpp v52, v53, v53 quad_perm:[2,3,0,1] row_mask:0xf bank_mask:0xf bound_ctrl:1
	v_mov_b32_e32 v53, 0
	s_nop 0
	v_add_f32_dpp v52, v52, v52 row_half_mirror row_mask:0xf bank_mask:0xf bound_ctrl:1
	s_nop 1
	v_add_f32_dpp v52, v52, v52 row_mirror row_mask:0xf bank_mask:0xf bound_ctrl:1
	s_nop 1
	v_mov_b32_dpp v53, v52 row_bcast:15 row_mask:0xa bank_mask:0xf
	v_add_f32_e32 v52, v52, v53
	v_mov_b32_e32 v53, 0
	s_nop 1
	v_mov_b32_dpp v53, v52 row_bcast:31 row_mask:0xc bank_mask:0xf
	v_add_f32_e32 v57, v52, v53
	ds_read_b128 v[52:55], v56
	ds_read_b128 v[58:61], v56 offset:2064
	ds_read_b128 v[62:65], v56 offset:2048
	ds_read_b128 v[66:69], v56 offset:16
	v_readlane_b32 s39, v57, 63
	s_waitcnt lgkmcnt(3)
	v_mul_f32_e32 v53, v31, v53
	v_fmac_f32_e32 v53, v30, v52
	v_mul_f32_e32 v52, v33, v55
	v_fmac_f32_e32 v52, v32, v54
	v_add_f32_e32 v52, v53, v52
	s_waitcnt lgkmcnt(0)
; #define LAS __attribute__((address_space(3)))
; __device__ __forceinline__ float wave_sum(float v) { return rdlane(dpp_sum63(v), 63); }
; __device__ __forceinline__ void row_finalize(CArgs& A, Frame& F, int m, const f32x4 (&v)[4], int Ln) {
;     ...
;     for (int c = 0; c < 8; ++c) { float s = 0.f;
; #pragma unroll
;         for (int j = 0; j < 4; ++j) { const f32x4 w = *(const LAS f32x4*)(wig + c * 1024 + RCOL(F.lane, j)); s += (v[j][0] * w[0] + v[j][1] * w[1]) + (v[j][2] * w[2] + v[j][3] * w[3]); }
;         r[c] = wave_sum(s); if (c & 1) asm volatile("" ::: "memory"); }
	v_mul_f32_e32 v53, v27, v67
	v_mul_f32_e32 v54, v29, v69
	v_fmac_f32_e32 v53, v26, v66
	v_fmac_f32_e32 v54, v28, v68
	v_add_f32_e32 v52, 0, v52
	v_add_f32_e32 v53, v53, v54
	v_add_f32_e32 v52, v53, v52
	v_mul_f32_e32 v53, v23, v63
	v_mul_f32_e32 v54, v25, v65
	v_fmac_f32_e32 v53, v22, v62
	v_fmac_f32_e32 v54, v24, v64
	v_add_f32_e32 v53, v53, v54
	v_add_f32_e32 v52, v53, v52
	v_mul_f32_e32 v53, v19, v59
	v_mul_f32_e32 v54, v21, v61
	v_fmac_f32_e32 v53, v18, v58
	v_fmac_f32_e32 v54, v20, v60
	v_add_f32_e32 v53, v53, v54
	v_add_f32_e32 v52, v53, v52
	v_mov_b32_e32 v53, 0
	v_mov_b32_e32 v54, 0
	v_add_f32_dpp v52, v52, v52 quad_perm:[1,0,3,2] row_mask:0xf bank_mask:0xf bound_ctrl:1
	s_nop 1
	v_add_f32_dpp v52, v52, v52 quad_perm:[2,3,0,1] row_mask:0xf bank_mask:0xf bound_ctrl:1
	s_nop 1
	v_add_f32_dpp v52, v52, v52 row_half_mirror row_mask:0xf bank_mask:0xf bound_ctrl:1
	s_nop 1
	v_add_f32_dpp v52, v52, v52 row_mirror row_mask:0xf bank_mask:0xf bound_ctrl:1
	s_nop 1
	v_mov_b32_dpp v53, v52 row_bcast:15 row_mask:0xa bank_mask:0xf
	v_add_f32_e32 v53, v52, v53
	v_add_u32_e32 v52, 0x15000, v35
	ds_read_b128 v[58:61], v52
	ds_read_b128 v[62:65], v52 offset:16
	v_mov_b32_dpp v54, v53 row_bcast:31 row_mask:0xc bank_mask:0xf
	v_add_f32_e32 v53, v53, v54
	s_waitcnt lgkmcnt(1)
	v_mul_f32_e32 v54, v33, v61
	v_readlane_b32 s40, v53, 63
	v_mul_f32_e32 v53, v31, v59
	v_fmac_f32_e32 v53, v30, v58
	v_fmac_f32_e32 v54, v32, v60
	ds_read_b128 v[58:61], v52 offset:2048
	v_add_f32_e32 v53, v53, v54
	s_waitcnt lgkmcnt(1)
	v_mul_f32_e32 v54, v27, v63
	v_mul_f32_e32 v55, v29, v65
	v_fmac_f32_e32 v54, v26, v62
	v_fmac_f32_e32 v55, v28, v64
	ds_read_b128 v[62:65], v52 offset:2064
	v_add_f32_e32 v53, 0, v53
	v_add_f32_e32 v54, v54, v55
	v_add_f32_e32 v53, v53, v54
	s_waitcnt lgkmcnt(1)
	v_mul_f32_e32 v54, v23, v59
	v_mul_f32_e32 v55, v25, v61
	v_fmac_f32_e32 v54, v22, v58
	v_fmac_f32_e32 v55, v24, v60
	v_add_f32_e32 v54, v54, v55
	v_add_f32_e32 v53, v53, v54
	s_waitcnt lgkmcnt(0)
	v_mul_f32_e32 v54, v19, v63
	v_mul_f32_e32 v55, v21, v65
	v_fmac_f32_e32 v54, v18, v62
	v_fmac_f32_e32 v55, v20, v64
	v_add_f32_e32 v54, v54, v55
	v_add_f32_e32 v53, v53, v54
	v_mov_b32_e32 v54, 0
	v_mov_b32_e32 v55, 0
	v_add_f32_dpp v53, v53, v53 quad_perm:[1,0,3,2] row_mask:0xf bank_mask:0xf bound_ctrl:1
	s_nop 1
	v_add_f32_dpp v53, v53, v53 quad_perm:[2,3,0,1] row_mask:0xf bank_mask:0xf bound_ctrl:1
	s_nop 1
	v_add_f32_dpp v53, v53, v53 row_half_mirror row_mask:0xf bank_mask:0xf bound_ctrl:1
	s_nop 1
	v_add_f32_dpp v53, v53, v53 row_mirror row_mask:0xf bank_mask:0xf bound_ctrl:1
	s_nop 1
	v_mov_b32_dpp v54, v53 row_bcast:15 row_mask:0xa bank_mask:0xf
	v_add_f32_e32 v54, v53, v54
	v_add_u32_e32 v53, 0x16000, v35
	ds_read_b128 v[58:61], v53
	ds_read_b128 v[62:65], v53 offset:16
	v_mov_b32_dpp v55, v54 row_bcast:31 row_mask:0xc bank_mask:0xf
	v_add_f32_e32 v54, v54, v55
	s_waitcnt lgkmcnt(1)
	v_mul_f32_e32 v55, v33, v61
	v_readlane_b32 s41, v54, 63
	v_mul_f32_e32 v54, v31, v59
	v_fmac_f32_e32 v54, v30, v58
	v_fmac_f32_e32 v55, v32, v60
	ds_read_b128 v[58:61], v53 offset:2048
	v_add_f32_e32 v54, v54, v55
	s_waitcnt lgkmcnt(1)
	v_mul_f32_e32 v55, v27, v63
	v_mul_f32_e32 v57, v29, v65
	v_fmac_f32_e32 v55, v26, v62
	v_fmac_f32_e32 v57, v28, v64
	ds_read_b128 v[62:65], v53 offset:2064
	v_add_f32_e32 v54, 0, v54
	v_add_f32_e32 v55, v55, v57
	v_add_f32_e32 v54, v54, v55
	s_waitcnt lgkmcnt(1)
	v_mul_f32_e32 v55, v23, v59
	v_mul_f32_e32 v57, v25, v61
	v_fmac_f32_e32 v55, v22, v58
	v_fmac_f32_e32 v57, v24, v60
	v_add_f32_e32 v55, v55, v57
	v_add_f32_e32 v54, v54, v55
	s_waitcnt lgkmcnt(0)
	v_mul_f32_e32 v55, v19, v63
	v_mul_f32_e32 v57, v21, v65
	v_fmac_f32_e32 v55, v18, v62
	v_fmac_f32_e32 v57, v20, v64
	v_add_f32_e32 v55, v55, v57
	v_add_f32_e32 v54, v54, v55
	v_mov_b32_e32 v55, 0
	v_mov_b32_e32 v57, 0
	v_add_f32_dpp v54, v54, v54 quad_perm:[1,0,3,2] row_mask:0xf bank_mask:0xf bound_ctrl:1
	s_nop 1
	v_add_f32_dpp v54, v54, v54 quad_perm:[2,3,0,1] row_mask:0xf bank_mask:0xf bound_ctrl:1
	s_nop 1
	v_add_f32_dpp v54, v54, v54 row_half_mirror row_mask:0xf bank_mask:0xf bound_ctrl:1
	s_nop 1
	v_add_f32_dpp v54, v54, v54 row_mirror row_mask:0xf bank_mask:0xf bound_ctrl:1
	s_nop 1
	v_mov_b32_dpp v55, v54 row_bcast:15 row_mask:0xa bank_mask:0xf
	v_add_f32_e32 v55, v54, v55
	v_add_u32_e32 v54, 0x17000, v35
	ds_read_b128 v[58:61], v54
	ds_read_b128 v[62:65], v54 offset:16
	v_mov_b32_dpp v57, v55 row_bcast:31 row_mask:0xc bank_mask:0xf
	v_add_f32_e32 v55, v55, v57
	s_waitcnt lgkmcnt(1)
	v_mul_f32_e32 v57, v33, v61
	v_readlane_b32 s42, v55, 63
	v_mul_f32_e32 v55, v31, v59
	v_fmac_f32_e32 v55, v30, v58
	v_fmac_f32_e32 v57, v32, v60
	ds_read_b128 v[58:61], v54 offset:2048
	v_add_f32_e32 v55, v55, v57
	s_waitcnt lgkmcnt(1)
	v_mul_f32_e32 v57, v27, v63
	v_fmac_f32_e32 v57, v26, v62
	v_mul_f32_e32 v62, v29, v65
	v_fmac_f32_e32 v62, v28, v64
	v_add_f32_e32 v55, 0, v55
	v_add_f32_e32 v57, v57, v62
	ds_read_b128 v[62:65], v54 offset:2064
	v_add_f32_e32 v55, v55, v57
	s_waitcnt lgkmcnt(1)
	v_mul_f32_e32 v57, v23, v59
	v_fmac_f32_e32 v57, v22, v58
	v_mul_f32_e32 v58, v25, v61
	v_fmac_f32_e32 v58, v24, v60
	v_add_f32_e32 v57, v57, v58
	v_add_f32_e32 v55, v55, v57
	s_waitcnt lgkmcnt(0)
; #define LAS __attribute__((address_space(3)))
; __device__ __forceinline__ float wave_sum(float v) { return rdlane(dpp_sum63(v), 63); }
; __device__ __forceinline__ void row_finalize(CArgs& A, Frame& F, int m, const f32x4 (&v)[4], int Ln) {
;     ...
;     for (int c = 0; c < 8; ++c) { float s = 0.f;
; #pragma unroll
;         for (int j = 0; j < 4; ++j) { const f32x4 w = *(const LAS f32x4*)(wig + c * 1024 + RCOL(F.lane, j)); s += (v[j][0] * w[0] + v[j][1] * w[1]) + (v[j][2] * w[2] + v[j][3] * w[3]); }
;         r[c] = wave_sum(s); if (c & 1) asm volatile("" ::: "memory"); }
;     if (F.lane < 8) { float x = r[0];
; #pragma unroll
;         for (int c = 1; c < 8; ++c) x = (F.lane == c) ? r[c] : x;
;         WSP(float, WS_IGFG)[(size_t)m * 8 + F.lane] = x + b_in[F.lane]; }
	v_mul_f32_e32 v57, v19, v63
	v_mul_f32_e32 v58, v21, v65
	v_fmac_f32_e32 v57, v18, v62
	v_fmac_f32_e32 v58, v20, v64
	v_add_f32_e32 v57, v57, v58
	v_add_f32_e32 v55, v55, v57
	v_mov_b32_e32 v57, 0
	s_nop 0
	v_add_f32_dpp v55, v55, v55 quad_perm:[1,0,3,2] row_mask:0xf bank_mask:0xf bound_ctrl:1
	s_nop 1
	v_add_f32_dpp v55, v55, v55 quad_perm:[2,3,0,1] row_mask:0xf bank_mask:0xf bound_ctrl:1
	s_nop 1
	v_add_f32_dpp v55, v55, v55 row_half_mirror row_mask:0xf bank_mask:0xf bound_ctrl:1
	s_nop 1
	v_add_f32_dpp v55, v55, v55 row_mirror row_mask:0xf bank_mask:0xf bound_ctrl:1
	s_nop 1
	v_mov_b32_dpp v57, v55 row_bcast:15 row_mask:0xa bank_mask:0xf
	v_add_f32_e32 v55, v55, v57
	v_mov_b32_e32 v57, 0
	s_nop 1
	v_mov_b32_dpp v57, v55 row_bcast:31 row_mask:0xc bank_mask:0xf
	v_add_f32_e32 v55, v55, v57
	v_add_u32_e32 v57, 0x18000, v35
	ds_read_b128 v[58:61], v57
	ds_read_b128 v[62:65], v57 offset:2064
	ds_read_b128 v[66:69], v57 offset:2048
	ds_read_b128 v[70:73], v57 offset:16
	v_readlane_b32 s43, v55, 63
	s_waitcnt lgkmcnt(3)
	v_mul_f32_e32 v55, v31, v59
	v_fmac_f32_e32 v55, v30, v58
	v_mul_f32_e32 v58, v33, v61
	v_fmac_f32_e32 v58, v32, v60
	v_add_f32_e32 v55, v55, v58
	s_waitcnt lgkmcnt(0)
	v_mul_f32_e32 v58, v27, v71
	v_mul_f32_e32 v59, v29, v73
	v_fmac_f32_e32 v58, v26, v70
	v_fmac_f32_e32 v59, v28, v72
	v_add_f32_e32 v55, 0, v55
	v_add_f32_e32 v58, v58, v59
	v_add_f32_e32 v55, v58, v55
	v_mul_f32_e32 v58, v23, v67
	v_mul_f32_e32 v59, v25, v69
	v_fmac_f32_e32 v58, v22, v66
	v_fmac_f32_e32 v59, v24, v68
	v_add_f32_e32 v58, v58, v59
	v_add_f32_e32 v55, v58, v55
	v_mul_f32_e32 v58, v19, v63
	v_mul_f32_e32 v59, v21, v65
	v_fmac_f32_e32 v58, v18, v62
	v_fmac_f32_e32 v59, v20, v64
	v_add_f32_e32 v58, v58, v59
	v_add_f32_e32 v55, v58, v55
	v_mov_b32_e32 v58, 0
	v_mov_b32_e32 v63, 0
	v_add_f32_dpp v55, v55, v55 quad_perm:[1,0,3,2] row_mask:0xf bank_mask:0xf bound_ctrl:1
	s_nop 1
	v_add_f32_dpp v55, v55, v55 quad_perm:[2,3,0,1] row_mask:0xf bank_mask:0xf bound_ctrl:1
	s_nop 1
	v_add_f32_dpp v55, v55, v55 row_half_mirror row_mask:0xf bank_mask:0xf bound_ctrl:1
	s_nop 1
	v_add_f32_dpp v55, v55, v55 row_mirror row_mask:0xf bank_mask:0xf bound_ctrl:1
	s_nop 1
	v_mov_b32_dpp v58, v55 row_bcast:15 row_mask:0xa bank_mask:0xf
	v_add_f32_e32 v62, v55, v58
	v_add_u32_e32 v55, 0x19000, v35
	ds_read_b128 v[58:61], v55
	v_mov_b32_dpp v63, v62 row_bcast:31 row_mask:0xc bank_mask:0xf
	v_add_f32_e32 v62, v62, v63
	s_nop 0
	v_readlane_b32 s44, v62, 63
	ds_read_b128 v[62:65], v55 offset:16
	s_waitcnt lgkmcnt(1)
	v_mul_f32_e32 v31, v31, v59
	v_fmac_f32_e32 v31, v30, v58
	v_mul_f32_e32 v30, v33, v61
	v_fmac_f32_e32 v30, v32, v60
	s_waitcnt lgkmcnt(0)
	v_mul_f32_e32 v27, v27, v63
	v_fmac_f32_e32 v27, v26, v62
	v_mul_f32_e32 v26, v29, v65
	v_add_f32_e32 v30, v31, v30
	v_fmac_f32_e32 v26, v28, v64
	v_add_f32_e32 v58, 0, v30
	ds_read_b128 v[30:33], v55 offset:2048
	v_add_f32_e32 v26, v27, v26
	v_add_f32_e32 v58, v58, v26
	ds_read_b128 v[26:29], v55 offset:2064
	s_waitcnt lgkmcnt(1)
	v_mul_f32_e32 v23, v23, v31
	v_fmac_f32_e32 v23, v22, v30
	v_mul_f32_e32 v22, v25, v33
	s_waitcnt lgkmcnt(0)
	v_mul_f32_e32 v19, v19, v27
	v_fmac_f32_e32 v22, v24, v32
	v_fmac_f32_e32 v19, v18, v26
	v_mul_f32_e32 v18, v21, v29
	v_add_f32_e32 v22, v23, v22
	v_fmac_f32_e32 v18, v20, v28
	v_add_f32_e32 v22, v58, v22
	v_add_f32_e32 v18, v19, v18
	v_add_f32_e32 v18, v22, v18
	v_mov_b32_e32 v19, 0
	s_nop 0
	v_add_f32_dpp v18, v18, v18 quad_perm:[1,0,3,2] row_mask:0xf bank_mask:0xf bound_ctrl:1
	s_nop 1
	v_add_f32_dpp v18, v18, v18 quad_perm:[2,3,0,1] row_mask:0xf bank_mask:0xf bound_ctrl:1
	s_nop 1
	v_add_f32_dpp v18, v18, v18 row_half_mirror row_mask:0xf bank_mask:0xf bound_ctrl:1
	s_nop 1
	v_add_f32_dpp v18, v18, v18 row_mirror row_mask:0xf bank_mask:0xf bound_ctrl:1
	s_nop 1
	v_mov_b32_dpp v19, v18 row_bcast:15 row_mask:0xa bank_mask:0xf
	v_add_f32_e32 v18, v18, v19
	v_mov_b32_e32 v19, 0
	s_nop 1
	v_mov_b32_dpp v19, v18 row_bcast:31 row_mask:0xc bank_mask:0xf
	v_add_f32_e32 v18, v18, v19
	s_nop 0
	v_readlane_b32 s45, v18, 63
	s_and_saveexec_b64 s[36:37], vcc
	s_cbranch_execz .LBB0_13
	v_mov_b32_e32 v18, v149
	v_mov_b32_e32 v19, s27
	v_mov_b32_e32 v20, s39
	v_cndmask_b32_e64 v19, v19, v20, s[16:17]
	v_mov_b32_e32 v20, s40
	v_cndmask_b32_e64 v19, v19, v20, s[4:5]
	v_mov_b32_e32 v20, s41
	v_cndmask_b32_e64 v19, v19, v20, s[6:7]
	v_mov_b32_e32 v20, s42
	v_cndmask_b32_e64 v19, v19, v20, s[8:9]
	v_mov_b32_e32 v20, s43
	v_cndmask_b32_e64 v19, v19, v20, s[10:11]
	v_mov_b32_e32 v20, s44
	v_cndmask_b32_e64 v19, v19, v20, s[12:13]
	v_mov_b32_e32 v20, s45
	v_cndmask_b32_e64 v19, v19, v20, s[14:15]
	s_nop 0
	v_add_f32_e32 v18, v19, v18
	global_store_dword v[48:49], v18, off
; #define LAS __attribute__((address_space(3)))
; __device__ __forceinline__ float wave_sum(float v) { return rdlane(dpp_sum63(v), 63); }
; __device__ __forceinline__ void row_finalize(CArgs& A, Frame& F, int m, const f32x4 (&v)[4], int Ln) {
;     row_store_bf(WSP(bf16, WS_X) + (size_t)m * D, F.lane, v);
;     const LAS float* wig = (const LAS float*)(F.lds + WIG_OFF); const float* b_in = A.in[10] + (size_t)Ln * DIN + 3072;
;     float r[8];
; #pragma unroll
;     for (int c = 0; c < 8; ++c) { float s = 0.f;
; #pragma unroll
;         for (int j = 0; j < 4; ++j) { const f32x4 w = *(const LAS f32x4*)(wig + c * 1024 + RCOL(F.lane, j)); s += (v[j][0] * w[0] + v[j][1] * w[1]) + (v[j][2] * w[2] + v[j][3] * w[3]); }
;         r[c] = wave_sum(s); if (c & 1) asm volatile("" ::: "memory"); }
.LBB0_13:
	s_or_b64 exec, exec, s[36:37]
	s_lshl_b64 s[36:37], s[34:35], 11
	v_lshl_add_u64 v[26:27], v[40:41], 0, s[36:37]
	s_waitcnt vmcnt(4)
	v_cvt_pk_bf16_f32 v18, v14, v15
	v_cvt_pk_bf16_f32 v19, v16, v17
	v_cvt_pk_bf16_f32 v20, v10, v11
	v_cvt_pk_bf16_f32 v21, v12, v13
	global_store_dwordx4 v[26:27], v[18:21], off
	s_waitcnt vmcnt(3)
	s_nop 0
	v_cvt_pk_bf16_f32 v18, v6, v7
	v_cvt_pk_bf16_f32 v19, v8, v9
	v_cvt_pk_bf16_f32 v20, v2, v3
	v_cvt_pk_bf16_f32 v21, v4, v5
	ds_read_b128 v[22:25], v39
	global_store_dwordx4 v[26:27], v[18:21], off offset:1024
	ds_read_b128 v[18:21], v39 offset:16
	s_waitcnt lgkmcnt(1)
	v_mul_f32_e32 v23, v15, v23
	v_fmac_f32_e32 v23, v14, v22
	v_mul_f32_e32 v22, v17, v25
	s_waitcnt lgkmcnt(0)
	v_mul_f32_e32 v19, v11, v19
	v_fmac_f32_e32 v22, v16, v24
	v_fmac_f32_e32 v19, v10, v18
	v_mul_f32_e32 v18, v13, v21
	v_add_f32_e32 v22, v23, v22
	v_fmac_f32_e32 v18, v12, v20
	v_add_f32_e32 v26, 0, v22
	ds_read_b128 v[22:25], v39 offset:2048
	v_add_f32_e32 v18, v19, v18
	v_add_f32_e32 v26, v26, v18
	ds_read_b128 v[18:21], v39 offset:2064
	s_waitcnt lgkmcnt(1)
	v_mul_f32_e32 v23, v7, v23
	v_fmac_f32_e32 v23, v6, v22
	v_mul_f32_e32 v22, v9, v25
	s_waitcnt lgkmcnt(0)
	v_mul_f32_e32 v19, v3, v19
	v_fmac_f32_e32 v22, v8, v24
	v_fmac_f32_e32 v19, v2, v18
	v_mul_f32_e32 v18, v5, v21
	v_add_f32_e32 v22, v23, v22
	v_fmac_f32_e32 v18, v4, v20
	v_add_f32_e32 v22, v26, v22
	v_add_f32_e32 v18, v19, v18
	v_add_f32_e32 v18, v22, v18
	v_mov_b32_e32 v19, 0
	v_mov_b32_e32 v23, 0
	v_add_f32_dpp v18, v18, v18 quad_perm:[1,0,3,2] row_mask:0xf bank_mask:0xf bound_ctrl:1
	s_nop 1
	v_add_f32_dpp v18, v18, v18 quad_perm:[2,3,0,1] row_mask:0xf bank_mask:0xf bound_ctrl:1
	s_nop 1
	v_add_f32_dpp v18, v18, v18 row_half_mirror row_mask:0xf bank_mask:0xf bound_ctrl:1
	s_nop 1
	v_add_f32_dpp v18, v18, v18 row_mirror row_mask:0xf bank_mask:0xf bound_ctrl:1
	s_nop 1
	v_mov_b32_dpp v19, v18 row_bcast:15 row_mask:0xa bank_mask:0xf
	v_add_f32_e32 v22, v18, v19
	ds_read_b128 v[18:21], v37
	s_nop 0
	v_mov_b32_dpp v23, v22 row_bcast:31 row_mask:0xc bank_mask:0xf
	v_add_f32_e32 v22, v22, v23
	s_nop 0
	v_readlane_b32 s27, v22, 63
	ds_read_b128 v[22:25], v37 offset:16
	s_waitcnt lgkmcnt(1)
	v_mul_f32_e32 v19, v15, v19
	v_fmac_f32_e32 v19, v14, v18
	v_mul_f32_e32 v18, v17, v21
	v_fmac_f32_e32 v18, v16, v20
	v_add_f32_e32 v18, v19, v18
	s_waitcnt lgkmcnt(0)
	v_mul_f32_e32 v23, v11, v23
	v_add_f32_e32 v26, 0, v18
	v_fmac_f32_e32 v23, v10, v22
	v_mul_f32_e32 v22, v13, v25
	ds_read_b128 v[18:21], v37 offset:2048
	v_fmac_f32_e32 v22, v12, v24
	v_add_f32_e32 v22, v23, v22
	v_add_f32_e32 v26, v26, v22
	ds_read_b128 v[22:25], v37 offset:2064
	s_waitcnt lgkmcnt(1)
	v_mul_f32_e32 v19, v7, v19
	v_fmac_f32_e32 v19, v6, v18
	v_mul_f32_e32 v18, v9, v21
	v_fmac_f32_e32 v18, v8, v20
	v_add_f32_e32 v18, v19, v18
	s_waitcnt lgkmcnt(0)
	v_mul_f32_e32 v19, v3, v23
	v_mul_f32_e32 v20, v5, v25
	v_fmac_f32_e32 v19, v2, v22
	v_fmac_f32_e32 v20, v4, v24
	v_add_f32_e32 v18, v26, v18
	v_add_f32_e32 v19, v19, v20
	v_add_f32_e32 v18, v18, v19
	v_mov_b32_e32 v19, 0
	s_nop 0
	v_add_f32_dpp v18, v18, v18 quad_perm:[1,0,3,2] row_mask:0xf bank_mask:0xf bound_ctrl:1
	s_nop 1
	v_add_f32_dpp v18, v18, v18 quad_perm:[2,3,0,1] row_mask:0xf bank_mask:0xf bound_ctrl:1
	s_nop 1
	v_add_f32_dpp v18, v18, v18 row_half_mirror row_mask:0xf bank_mask:0xf bound_ctrl:1
	s_nop 1
	v_add_f32_dpp v18, v18, v18 row_mirror row_mask:0xf bank_mask:0xf bound_ctrl:1
	s_nop 1
	v_mov_b32_dpp v19, v18 row_bcast:15 row_mask:0xa bank_mask:0xf
	v_add_f32_e32 v18, v18, v19
	v_mov_b32_e32 v19, 0
	s_nop 1
	v_mov_b32_dpp v19, v18 row_bcast:31 row_mask:0xc bank_mask:0xf
	v_add_f32_e32 v22, v18, v19
	ds_read_b128 v[18:21], v56
	v_readlane_b32 s39, v22, 63
	ds_read_b128 v[22:25], v56 offset:2064
	ds_read_b128 v[26:29], v56 offset:2048
	ds_read_b128 v[30:33], v56 offset:16
	s_waitcnt lgkmcnt(3)
	v_mul_f32_e32 v19, v15, v19
	v_fmac_f32_e32 v19, v14, v18
	v_mul_f32_e32 v18, v17, v21
	v_fmac_f32_e32 v18, v16, v20
	v_add_f32_e32 v18, v19, v18
	s_waitcnt lgkmcnt(0)
	v_mul_f32_e32 v19, v11, v31
	v_mul_f32_e32 v20, v13, v33
	v_fmac_f32_e32 v19, v10, v30
	v_fmac_f32_e32 v20, v12, v32
	v_add_f32_e32 v18, 0, v18
	v_add_f32_e32 v19, v19, v20
	v_add_f32_e32 v18, v19, v18
	v_mul_f32_e32 v19, v7, v27
	v_mul_f32_e32 v20, v9, v29
	v_fmac_f32_e32 v19, v6, v26
	v_fmac_f32_e32 v20, v8, v28
	v_add_f32_e32 v19, v19, v20
	v_add_f32_e32 v18, v19, v18
	v_mul_f32_e32 v19, v3, v23
	v_mul_f32_e32 v20, v5, v25
	v_fmac_f32_e32 v19, v2, v22
	v_fmac_f32_e32 v20, v4, v24
	v_add_f32_e32 v19, v19, v20
	v_add_f32_e32 v18, v19, v18
	v_mov_b32_e32 v19, 0
	v_mov_b32_e32 v23, 0
	v_add_f32_dpp v18, v18, v18 quad_perm:[1,0,3,2] row_mask:0xf bank_mask:0xf bound_ctrl:1
	s_nop 1
	v_add_f32_dpp v18, v18, v18 quad_perm:[2,3,0,1] row_mask:0xf bank_mask:0xf bound_ctrl:1
	s_nop 1
	v_add_f32_dpp v18, v18, v18 row_half_mirror row_mask:0xf bank_mask:0xf bound_ctrl:1
	s_nop 1
	v_add_f32_dpp v18, v18, v18 row_mirror row_mask:0xf bank_mask:0xf bound_ctrl:1
	s_nop 1
	v_mov_b32_dpp v19, v18 row_bcast:15 row_mask:0xa bank_mask:0xf
	v_add_f32_e32 v22, v18, v19
	ds_read_b128 v[18:21], v52
	s_nop 0
	v_mov_b32_dpp v23, v22 row_bcast:31 row_mask:0xc bank_mask:0xf
	v_add_f32_e32 v22, v22, v23
	s_nop 0
	v_readlane_b32 s40, v22, 63
	ds_read_b128 v[22:25], v52 offset:16
	s_waitcnt lgkmcnt(1)
	v_mul_f32_e32 v19, v15, v19
	v_fmac_f32_e32 v19, v14, v18
	v_mul_f32_e32 v18, v17, v21
	v_fmac_f32_e32 v18, v16, v20
	v_add_f32_e32 v18, v19, v18
	s_waitcnt lgkmcnt(0)
; #define LAS __attribute__((address_space(3)))
; __device__ __forceinline__ float wave_sum(float v) { return rdlane(dpp_sum63(v), 63); }
; __device__ __forceinline__ void row_finalize(CArgs& A, Frame& F, int m, const f32x4 (&v)[4], int Ln) {
;     ...
;     for (int c = 0; c < 8; ++c) { float s = 0.f;
; #pragma unroll
;         for (int j = 0; j < 4; ++j) { const f32x4 w = *(const LAS f32x4*)(wig + c * 1024 + RCOL(F.lane, j)); s += (v[j][0] * w[0] + v[j][1] * w[1]) + (v[j][2] * w[2] + v[j][3] * w[3]); }
;         r[c] = wave_sum(s); if (c & 1) asm volatile("" ::: "memory"); }
	v_mul_f32_e32 v23, v11, v23
	v_add_f32_e32 v26, 0, v18
	v_fmac_f32_e32 v23, v10, v22
	v_mul_f32_e32 v22, v13, v25
	ds_read_b128 v[18:21], v52 offset:2048
	v_fmac_f32_e32 v22, v12, v24
	v_add_f32_e32 v22, v23, v22
	v_add_f32_e32 v26, v26, v22
	ds_read_b128 v[22:25], v52 offset:2064
	s_waitcnt lgkmcnt(1)
	v_mul_f32_e32 v19, v7, v19
	v_fmac_f32_e32 v19, v6, v18
	v_mul_f32_e32 v18, v9, v21
	v_fmac_f32_e32 v18, v8, v20
	v_add_f32_e32 v18, v19, v18
	s_waitcnt lgkmcnt(0)
	v_mul_f32_e32 v19, v3, v23
	v_mul_f32_e32 v20, v5, v25
	v_fmac_f32_e32 v19, v2, v22
	v_fmac_f32_e32 v20, v4, v24
	v_add_f32_e32 v18, v26, v18
	v_add_f32_e32 v19, v19, v20
	v_add_f32_e32 v18, v18, v19
	v_mov_b32_e32 v19, 0
	v_mov_b32_e32 v23, 0
	v_add_f32_dpp v18, v18, v18 quad_perm:[1,0,3,2] row_mask:0xf bank_mask:0xf bound_ctrl:1
	s_nop 1
	v_add_f32_dpp v18, v18, v18 quad_perm:[2,3,0,1] row_mask:0xf bank_mask:0xf bound_ctrl:1
	s_nop 1
	v_add_f32_dpp v18, v18, v18 row_half_mirror row_mask:0xf bank_mask:0xf bound_ctrl:1
	s_nop 1
	v_add_f32_dpp v18, v18, v18 row_mirror row_mask:0xf bank_mask:0xf bound_ctrl:1
	s_nop 1
	v_mov_b32_dpp v19, v18 row_bcast:15 row_mask:0xa bank_mask:0xf
	v_add_f32_e32 v22, v18, v19
	ds_read_b128 v[18:21], v53
	s_nop 0
	v_mov_b32_dpp v23, v22 row_bcast:31 row_mask:0xc bank_mask:0xf
	v_add_f32_e32 v22, v22, v23
	s_nop 0
	v_readlane_b32 s41, v22, 63
	ds_read_b128 v[22:25], v53 offset:16
	s_waitcnt lgkmcnt(1)
	v_mul_f32_e32 v19, v15, v19
	v_fmac_f32_e32 v19, v14, v18
	v_mul_f32_e32 v18, v17, v21
	v_fmac_f32_e32 v18, v16, v20
	v_add_f32_e32 v18, v19, v18
	s_waitcnt lgkmcnt(0)
	v_mul_f32_e32 v23, v11, v23
	v_add_f32_e32 v26, 0, v18
	v_fmac_f32_e32 v23, v10, v22
	v_mul_f32_e32 v22, v13, v25
	ds_read_b128 v[18:21], v53 offset:2048
	v_fmac_f32_e32 v22, v12, v24
	v_add_f32_e32 v22, v23, v22
	v_add_f32_e32 v26, v26, v22
	ds_read_b128 v[22:25], v53 offset:2064
	s_waitcnt lgkmcnt(1)
	v_mul_f32_e32 v19, v7, v19
	v_fmac_f32_e32 v19, v6, v18
	v_mul_f32_e32 v18, v9, v21
	v_fmac_f32_e32 v18, v8, v20
	v_add_f32_e32 v18, v19, v18
	s_waitcnt lgkmcnt(0)
	v_mul_f32_e32 v19, v3, v23
	v_mul_f32_e32 v20, v5, v25
	v_fmac_f32_e32 v19, v2, v22
	v_fmac_f32_e32 v20, v4, v24
	v_add_f32_e32 v18, v26, v18
	v_add_f32_e32 v19, v19, v20
	v_add_f32_e32 v18, v18, v19
	v_mov_b32_e32 v19, 0
	v_mov_b32_e32 v23, 0
	v_add_f32_dpp v18, v18, v18 quad_perm:[1,0,3,2] row_mask:0xf bank_mask:0xf bound_ctrl:1
	s_nop 1
	v_add_f32_dpp v18, v18, v18 quad_perm:[2,3,0,1] row_mask:0xf bank_mask:0xf bound_ctrl:1
	s_nop 1
	v_add_f32_dpp v18, v18, v18 row_half_mirror row_mask:0xf bank_mask:0xf bound_ctrl:1
	s_nop 1
	v_add_f32_dpp v18, v18, v18 row_mirror row_mask:0xf bank_mask:0xf bound_ctrl:1
	s_nop 1
	v_mov_b32_dpp v19, v18 row_bcast:15 row_mask:0xa bank_mask:0xf
	v_add_f32_e32 v22, v18, v19
	ds_read_b128 v[18:21], v54
	s_nop 0
	v_mov_b32_dpp v23, v22 row_bcast:31 row_mask:0xc bank_mask:0xf
	v_add_f32_e32 v22, v22, v23
	s_nop 0
	v_readlane_b32 s42, v22, 63
	ds_read_b128 v[22:25], v54 offset:16
	s_waitcnt lgkmcnt(1)
	v_mul_f32_e32 v19, v15, v19
	v_fmac_f32_e32 v19, v14, v18
	v_mul_f32_e32 v18, v17, v21
	v_fmac_f32_e32 v18, v16, v20
	v_add_f32_e32 v18, v19, v18
	s_waitcnt lgkmcnt(0)
	v_mul_f32_e32 v23, v11, v23
	v_add_f32_e32 v26, 0, v18
	v_fmac_f32_e32 v23, v10, v22
	v_mul_f32_e32 v22, v13, v25
	ds_read_b128 v[18:21], v54 offset:2048
	v_fmac_f32_e32 v22, v12, v24
	v_add_f32_e32 v22, v23, v22
	v_add_f32_e32 v26, v26, v22
	ds_read_b128 v[22:25], v54 offset:2064
	s_waitcnt lgkmcnt(1)
	v_mul_f32_e32 v19, v7, v19
	v_fmac_f32_e32 v19, v6, v18
	v_mul_f32_e32 v18, v9, v21
	v_fmac_f32_e32 v18, v8, v20
	v_add_f32_e32 v18, v19, v18
	s_waitcnt lgkmcnt(0)
; #define LAS __attribute__((address_space(3)))
; __device__ __forceinline__ float wave_sum(float v) { return rdlane(dpp_sum63(v), 63); }
; __device__ __forceinline__ void row_finalize(CArgs& A, Frame& F, int m, const f32x4 (&v)[4], int Ln) {
;     ...
;     for (int c = 0; c < 8; ++c) { float s = 0.f;
; #pragma unroll
;         for (int j = 0; j < 4; ++j) { const f32x4 w = *(const LAS f32x4*)(wig + c * 1024 + RCOL(F.lane, j)); s += (v[j][0] * w[0] + v[j][1] * w[1]) + (v[j][2] * w[2] + v[j][3] * w[3]); }
;         r[c] = wave_sum(s); if (c & 1) asm volatile("" ::: "memory"); }
;     if (F.lane < 8) { float x = r[0];
; #pragma unroll
;         for (int c = 1; c < 8; ++c) x = (F.lane == c) ? r[c] : x;
;         WSP(float, WS_IGFG)[(size_t)m * 8 + F.lane] = x + b_in[F.lane]; }
	v_mul_f32_e32 v19, v3, v23
	v_mul_f32_e32 v20, v5, v25
	v_fmac_f32_e32 v19, v2, v22
	v_fmac_f32_e32 v20, v4, v24
	v_add_f32_e32 v18, v26, v18
	v_add_f32_e32 v19, v19, v20
	v_add_f32_e32 v18, v18, v19
	v_mov_b32_e32 v19, 0
	s_nop 0
	v_add_f32_dpp v18, v18, v18 quad_perm:[1,0,3,2] row_mask:0xf bank_mask:0xf bound_ctrl:1
	s_nop 1
	v_add_f32_dpp v18, v18, v18 quad_perm:[2,3,0,1] row_mask:0xf bank_mask:0xf bound_ctrl:1
	s_nop 1
	v_add_f32_dpp v18, v18, v18 row_half_mirror row_mask:0xf bank_mask:0xf bound_ctrl:1
	s_nop 1
	v_add_f32_dpp v18, v18, v18 row_mirror row_mask:0xf bank_mask:0xf bound_ctrl:1
	s_nop 1
	v_mov_b32_dpp v19, v18 row_bcast:15 row_mask:0xa bank_mask:0xf
	v_add_f32_e32 v18, v18, v19
	v_mov_b32_e32 v19, 0
	s_nop 1
	v_mov_b32_dpp v19, v18 row_bcast:31 row_mask:0xc bank_mask:0xf
	v_add_f32_e32 v22, v18, v19
	ds_read_b128 v[18:21], v57
	v_readlane_b32 s43, v22, 63
	ds_read_b128 v[22:25], v57 offset:2064
	ds_read_b128 v[26:29], v57 offset:2048
	ds_read_b128 v[30:33], v57 offset:16
	s_waitcnt lgkmcnt(3)
	v_mul_f32_e32 v19, v15, v19
	v_fmac_f32_e32 v19, v14, v18
	v_mul_f32_e32 v18, v17, v21
	v_fmac_f32_e32 v18, v16, v20
	v_add_f32_e32 v18, v19, v18
	s_waitcnt lgkmcnt(0)
	v_mul_f32_e32 v19, v11, v31
	v_mul_f32_e32 v20, v13, v33
	v_fmac_f32_e32 v19, v10, v30
	v_fmac_f32_e32 v20, v12, v32
	v_add_f32_e32 v18, 0, v18
	v_add_f32_e32 v19, v19, v20
	v_add_f32_e32 v18, v19, v18
	v_mul_f32_e32 v19, v7, v27
	v_mul_f32_e32 v20, v9, v29
	v_fmac_f32_e32 v19, v6, v26
	v_fmac_f32_e32 v20, v8, v28
	v_add_f32_e32 v19, v19, v20
	v_add_f32_e32 v18, v19, v18
	v_mul_f32_e32 v19, v3, v23
	v_mul_f32_e32 v20, v5, v25
	v_fmac_f32_e32 v19, v2, v22
	v_fmac_f32_e32 v20, v4, v24
	v_add_f32_e32 v19, v19, v20
	v_add_f32_e32 v18, v19, v18
	v_mov_b32_e32 v19, 0
	v_mov_b32_e32 v23, 0
	v_add_f32_dpp v18, v18, v18 quad_perm:[1,0,3,2] row_mask:0xf bank_mask:0xf bound_ctrl:1
	s_nop 1
	v_add_f32_dpp v18, v18, v18 quad_perm:[2,3,0,1] row_mask:0xf bank_mask:0xf bound_ctrl:1
	s_nop 1
	v_add_f32_dpp v18, v18, v18 row_half_mirror row_mask:0xf bank_mask:0xf bound_ctrl:1
	s_nop 1
	v_add_f32_dpp v18, v18, v18 row_mirror row_mask:0xf bank_mask:0xf bound_ctrl:1
	s_nop 1
	v_mov_b32_dpp v19, v18 row_bcast:15 row_mask:0xa bank_mask:0xf
	v_add_f32_e32 v22, v18, v19
	ds_read_b128 v[18:21], v55
	s_nop 0
	v_mov_b32_dpp v23, v22 row_bcast:31 row_mask:0xc bank_mask:0xf
	v_add_f32_e32 v22, v22, v23
	s_nop 0
	v_readlane_b32 s44, v22, 63
	ds_read_b128 v[22:25], v55 offset:16
	s_waitcnt lgkmcnt(1)
	v_mul_f32_e32 v15, v15, v19
	v_fmac_f32_e32 v15, v14, v18
	v_mul_f32_e32 v14, v17, v21
	v_fmac_f32_e32 v14, v16, v20
	s_waitcnt lgkmcnt(0)
	v_mul_f32_e32 v11, v11, v23
	v_fmac_f32_e32 v11, v10, v22
	v_mul_f32_e32 v10, v13, v25
	v_add_f32_e32 v14, v15, v14
	v_fmac_f32_e32 v10, v12, v24
	v_add_f32_e32 v18, 0, v14
	ds_read_b128 v[14:17], v55 offset:2048
	v_add_f32_e32 v10, v11, v10
	v_add_f32_e32 v18, v18, v10
	ds_read_b128 v[10:13], v55 offset:2064
	s_waitcnt lgkmcnt(1)
	v_mul_f32_e32 v7, v7, v15
	v_fmac_f32_e32 v7, v6, v14
	v_mul_f32_e32 v6, v9, v17
	s_waitcnt lgkmcnt(0)
	v_mul_f32_e32 v3, v3, v11
	v_fmac_f32_e32 v6, v8, v16
	v_fmac_f32_e32 v3, v2, v10
	v_mul_f32_e32 v2, v5, v13
	v_add_f32_e32 v6, v7, v6
	v_fmac_f32_e32 v2, v4, v12
	v_add_f32_e32 v6, v18, v6
	v_add_f32_e32 v2, v3, v2
	v_add_f32_e32 v2, v6, v2
	v_mov_b32_e32 v3, 0
	s_nop 0
	v_add_f32_dpp v2, v2, v2 quad_perm:[1,0,3,2] row_mask:0xf bank_mask:0xf bound_ctrl:1
	s_nop 1
	v_add_f32_dpp v2, v2, v2 quad_perm:[2,3,0,1] row_mask:0xf bank_mask:0xf bound_ctrl:1
	s_nop 1
	v_add_f32_dpp v2, v2, v2 row_half_mirror row_mask:0xf bank_mask:0xf bound_ctrl:1
	s_nop 1
	v_add_f32_dpp v2, v2, v2 row_mirror row_mask:0xf bank_mask:0xf bound_ctrl:1
	s_nop 1
	v_mov_b32_dpp v3, v2 row_bcast:15 row_mask:0xa bank_mask:0xf
	v_add_f32_e32 v2, v2, v3
	v_mov_b32_e32 v3, 0
	s_nop 1
	v_mov_b32_dpp v3, v2 row_bcast:31 row_mask:0xc bank_mask:0xf
	v_add_f32_e32 v2, v2, v3
	s_nop 0
	v_readlane_b32 s45, v2, 63
	s_and_saveexec_b64 s[36:37], vcc
	s_cbranch_execz .LBB0_10
	v_mov_b32_e32 v2, v149
	v_mov_b32_e32 v3, s27
	v_mov_b32_e32 v4, s39
	v_mov_b32_e32 v5, s40
	v_cndmask_b32_e64 v3, v3, v4, s[16:17]
	v_mov_b32_e32 v6, s41
	v_cndmask_b32_e64 v3, v3, v5, s[4:5]
	v_mov_b32_e32 v7, s42
	v_cndmask_b32_e64 v3, v3, v6, s[6:7]
	v_mov_b32_e32 v8, s43
	v_cndmask_b32_e64 v3, v3, v7, s[8:9]
	v_mov_b32_e32 v9, s44
	v_cndmask_b32_e64 v3, v3, v8, s[10:11]
	v_mov_b32_e32 v10, s45
	v_cndmask_b32_e64 v3, v3, v9, s[12:13]
	s_lshl_b64 s[34:35], s[34:35], 5
	v_cndmask_b32_e64 v3, v3, v10, s[14:15]
	s_nop 0
	v_add_f32_e32 v4, v3, v2
	v_lshl_add_u64 v[2:3], v[44:45], 0, s[34:35]
	global_store_dword v[2:3], v4, off
	s_branch .LBB0_10
